# previous + stream item tail no longer drains its own stores (hipcc's vmcnt(8) there protected the redundant last-trip loads, which the regenerated ring does not issue)
# baseline (speedup 1.0000x reference)
; __device__ __forceinline__ unsigned pk2(float lo, float hi) { unsigned r; asm("v_cvt_pk_bf16_f32 %0, %1, %2" : "=v"(r) : "v"(lo), "v"(hi)); return r; }
; __device__ __forceinline__ void ret_sample_item(Frame& F, int item) {
;     ...
;     if (fq < 2) {
; #pragma unroll
;         for (int j = 0; j < 4; ++j) { const int n = 4 * fq + j;
;             f32x4 o = (f32x4){oacc[0][j], oacc[1][j], oacc[2][j], oacc[3][j]} * gam;
; #pragma unroll
;             for (int m = 0; m < 8; ++m) o += pm[n * 8 + m] * v4[m];
;             u32x2 o2; o2.x = pk2(o[0], o[1]); o2.y = pk2(o[2], o[3]);
;             *(u32x2*)(WSP(bf16, WS_O) + (size_t)(r0 + n) * HV + h * DV + e4) = o2; }
;     }
.LBB0_618:
	s_and_saveexec_b64 s[78:79], s[2:3]
	s_cbranch_execz .LBB0_575
	s_nop 0
	ds_read_b128 v[34:37], v165 offset:34944
	ds_read_b128 v[38:41], v165 offset:34960
	v_mov_b32_e32 v42, v110
	v_mov_b32_e32 v43, v106
	s_lshl_b32 s22, s76, 1
	s_waitcnt lgkmcnt(1)
	v_pk_mul_f32 v[46:47], v[30:31], v[34:35] op_sel_hi:[1,0]
	v_pk_mul_f32 v[44:45], v[32:33], v[34:35] op_sel_hi:[1,0]
	v_pk_fma_f32 v[42:43], v[138:139], v[42:43], v[46:47] op_sel_hi:[0,1,1]
	v_mov_b32_e32 v46, v102
	v_mov_b32_e32 v47, v98
	v_pk_fma_f32 v[44:45], v[138:139], v[46:47], v[44:45] op_sel_hi:[0,1,1]
	v_pk_fma_f32 v[42:43], v[26:27], v[34:35], v[42:43] op_sel:[0,1,0]
	v_pk_fma_f32 v[34:35], v[28:29], v[34:35], v[44:45] op_sel:[0,1,0]
	v_pk_fma_f32 v[42:43], v[22:23], v[36:37], v[42:43] op_sel_hi:[1,0,1]
	v_pk_fma_f32 v[34:35], v[24:25], v[36:37], v[34:35] op_sel_hi:[1,0,1]
	v_mov_b32_e32 v36, v37
	v_pk_fma_f32 v[34:35], v[20:21], v[36:37], v[34:35] op_sel_hi:[1,0,1]
	v_pk_fma_f32 v[42:43], v[18:19], v[36:37], v[42:43] op_sel_hi:[1,0,1]
	s_waitcnt lgkmcnt(0)
	v_pk_fma_f32 v[34:35], v[16:17], v[38:39], v[34:35] op_sel_hi:[1,0,1]
	v_pk_fma_f32 v[36:37], v[14:15], v[38:39], v[42:43] op_sel_hi:[1,0,1]
	v_pk_fma_f32 v[34:35], v[12:13], v[38:39], v[34:35] op_sel:[0,1,0]
	v_pk_fma_f32 v[36:37], v[10:11], v[38:39], v[36:37] op_sel:[0,1,0]
	v_pk_fma_f32 v[34:35], v[8:9], v[40:41], v[34:35] op_sel_hi:[1,0,1]
	v_mov_b32_e32 v38, v41
	v_pk_fma_f32 v[36:37], v[6:7], v[40:41], v[36:37] op_sel_hi:[1,0,1]
	v_pk_fma_f32 v[34:35], v[4:5], v[38:39], v[34:35] op_sel_hi:[1,0,1]
	v_pk_fma_f32 v[36:37], v[2:3], v[38:39], v[36:37] op_sel_hi:[1,0,1]
	v_cvt_pk_bf16_f32 v39, v34, v35
	v_or_b32_e32 v34, s91, v154
	v_ashrrev_i32_e32 v35, 31, v34
	v_lshlrev_b64 v[34:35], 13, v[34:35]
	v_cvt_pk_bf16_f32 v38, v36, v37
	v_lshl_add_u64 v[40:41], s[36:37], 0, v[34:35]
	ds_read_b128 v[34:37], v166 offset:34944
	v_lshl_add_u64 v[40:41], v[40:41], 0, s[22:23]
	v_lshl_add_u64 v[40:41], v[40:41], 0, v[134:135]
	global_store_dwordx2 v[40:41], v[38:39], off
	ds_read_b128 v[38:41], v166 offset:34960
	s_waitcnt lgkmcnt(1)
	v_pk_mul_f32 v[42:43], v[32:33], v[34:35] op_sel_hi:[1,0]
	v_pk_mul_f32 v[44:45], v[30:31], v[34:35] op_sel_hi:[1,0]
	v_mov_b32_e32 v106, v111
	v_mov_b32_e32 v98, v103
	v_pk_fma_f32 v[44:45], v[138:139], v[106:107], v[44:45] op_sel_hi:[0,1,1]
	v_pk_fma_f32 v[42:43], v[138:139], v[98:99], v[42:43] op_sel_hi:[0,1,1]
	v_pk_fma_f32 v[44:45], v[26:27], v[34:35], v[44:45] op_sel:[0,1,0]
	v_pk_fma_f32 v[34:35], v[28:29], v[34:35], v[42:43] op_sel:[0,1,0]
	v_pk_fma_f32 v[42:43], v[22:23], v[36:37], v[44:45] op_sel_hi:[1,0,1]
	v_pk_fma_f32 v[34:35], v[24:25], v[36:37], v[34:35] op_sel_hi:[1,0,1]
	v_mov_b32_e32 v36, v37
	v_pk_fma_f32 v[34:35], v[20:21], v[36:37], v[34:35] op_sel_hi:[1,0,1]
	v_pk_fma_f32 v[42:43], v[18:19], v[36:37], v[42:43] op_sel_hi:[1,0,1]
	s_waitcnt lgkmcnt(0)
	v_pk_fma_f32 v[34:35], v[16:17], v[38:39], v[34:35] op_sel_hi:[1,0,1]
	v_pk_fma_f32 v[36:37], v[14:15], v[38:39], v[42:43] op_sel_hi:[1,0,1]
	v_pk_fma_f32 v[34:35], v[12:13], v[38:39], v[34:35] op_sel:[0,1,0]
	v_pk_fma_f32 v[36:37], v[10:11], v[38:39], v[36:37] op_sel:[0,1,0]
	v_pk_fma_f32 v[34:35], v[8:9], v[40:41], v[34:35] op_sel_hi:[1,0,1]
	v_mov_b32_e32 v38, v41
	v_pk_fma_f32 v[36:37], v[6:7], v[40:41], v[36:37] op_sel_hi:[1,0,1]
	v_pk_fma_f32 v[34:35], v[4:5], v[38:39], v[34:35] op_sel_hi:[1,0,1]
	v_pk_fma_f32 v[36:37], v[2:3], v[38:39], v[36:37] op_sel_hi:[1,0,1]
	v_cvt_pk_bf16_f32 v39, v34, v35
	v_or_b32_e32 v34, s91, v155
	v_ashrrev_i32_e32 v35, 31, v34
	v_lshlrev_b64 v[34:35], 13, v[34:35]
	v_cvt_pk_bf16_f32 v38, v36, v37
	v_lshl_add_u64 v[40:41], s[36:37], 0, v[34:35]
	ds_read_b128 v[34:37], v167 offset:34944
	v_lshl_add_u64 v[40:41], v[40:41], 0, s[22:23]
	v_lshl_add_u64 v[40:41], v[40:41], 0, v[134:135]
	global_store_dwordx2 v[40:41], v[38:39], off
	ds_read_b128 v[38:41], v167 offset:34960
	s_waitcnt lgkmcnt(1)
; __device__ __forceinline__ unsigned pk2(float lo, float hi) { unsigned r; asm("v_cvt_pk_bf16_f32 %0, %1, %2" : "=v"(r) : "v"(lo), "v"(hi)); return r; }
; __device__ __forceinline__ void ret_sample_item(Frame& F, int item) {
;     ...
;     if (fq < 2) {
; #pragma unroll
;         for (int j = 0; j < 4; ++j) { const int n = 4 * fq + j;
;             f32x4 o = (f32x4){oacc[0][j], oacc[1][j], oacc[2][j], oacc[3][j]} * gam;
; #pragma unroll
;             for (int m = 0; m < 8; ++m) o += pm[n * 8 + m] * v4[m];
;             u32x2 o2; o2.x = pk2(o[0], o[1]); o2.y = pk2(o[2], o[3]);
;             *(u32x2*)(WSP(bf16, WS_O) + (size_t)(r0 + n) * HV + h * DV + e4) = o2; }
;     }
	v_pk_mul_f32 v[44:45], v[30:31], v[34:35] op_sel_hi:[1,0]
	v_mov_b32_e32 v46, v112
	v_mov_b32_e32 v47, v108
	v_pk_mul_f32 v[42:43], v[32:33], v[34:35] op_sel_hi:[1,0]
	v_pk_fma_f32 v[44:45], v[138:139], v[46:47], v[44:45] op_sel_hi:[0,1,1]
	v_mov_b32_e32 v46, v104
	v_mov_b32_e32 v47, v100
	v_pk_fma_f32 v[42:43], v[138:139], v[46:47], v[42:43] op_sel_hi:[0,1,1]
	v_pk_fma_f32 v[44:45], v[26:27], v[34:35], v[44:45] op_sel:[0,1,0]
	v_pk_fma_f32 v[34:35], v[28:29], v[34:35], v[42:43] op_sel:[0,1,0]
	v_pk_fma_f32 v[42:43], v[22:23], v[36:37], v[44:45] op_sel_hi:[1,0,1]
	v_pk_fma_f32 v[34:35], v[24:25], v[36:37], v[34:35] op_sel_hi:[1,0,1]
	v_mov_b32_e32 v36, v37
	v_pk_fma_f32 v[34:35], v[20:21], v[36:37], v[34:35] op_sel_hi:[1,0,1]
	v_pk_fma_f32 v[42:43], v[18:19], v[36:37], v[42:43] op_sel_hi:[1,0,1]
	s_waitcnt lgkmcnt(0)
	v_pk_fma_f32 v[34:35], v[16:17], v[38:39], v[34:35] op_sel_hi:[1,0,1]
	v_pk_fma_f32 v[36:37], v[14:15], v[38:39], v[42:43] op_sel_hi:[1,0,1]
	v_pk_fma_f32 v[34:35], v[12:13], v[38:39], v[34:35] op_sel:[0,1,0]
	v_pk_fma_f32 v[36:37], v[10:11], v[38:39], v[36:37] op_sel:[0,1,0]
	v_pk_fma_f32 v[34:35], v[8:9], v[40:41], v[34:35] op_sel_hi:[1,0,1]
	v_mov_b32_e32 v38, v41
	v_pk_fma_f32 v[36:37], v[6:7], v[40:41], v[36:37] op_sel_hi:[1,0,1]
	v_pk_fma_f32 v[34:35], v[4:5], v[38:39], v[34:35] op_sel_hi:[1,0,1]
	v_pk_fma_f32 v[36:37], v[2:3], v[38:39], v[36:37] op_sel_hi:[1,0,1]
	v_cvt_pk_bf16_f32 v39, v34, v35
	v_or_b32_e32 v34, s91, v156
	v_ashrrev_i32_e32 v35, 31, v34
	v_lshlrev_b64 v[34:35], 13, v[34:35]
	v_cvt_pk_bf16_f32 v38, v36, v37
	v_lshl_add_u64 v[40:41], s[36:37], 0, v[34:35]
	ds_read_b128 v[34:37], v168 offset:34944
	v_lshl_add_u64 v[40:41], v[40:41], 0, s[22:23]
	v_lshl_add_u64 v[40:41], v[40:41], 0, v[134:135]
	global_store_dwordx2 v[40:41], v[38:39], off
	ds_read_b128 v[38:41], v168 offset:34960
	s_waitcnt lgkmcnt(1)
	v_pk_mul_f32 v[32:33], v[32:33], v[34:35] op_sel_hi:[1,0]
	v_pk_mul_f32 v[30:31], v[30:31], v[34:35] op_sel_hi:[1,0]
	v_mov_b32_e32 v108, v113
	v_mov_b32_e32 v100, v105
	v_pk_fma_f32 v[30:31], v[138:139], v[108:109], v[30:31] op_sel_hi:[0,1,1]
	v_pk_fma_f32 v[32:33], v[138:139], v[100:101], v[32:33] op_sel_hi:[0,1,1]
	v_pk_fma_f32 v[26:27], v[26:27], v[34:35], v[30:31] op_sel:[0,1,0]
	v_pk_fma_f32 v[28:29], v[28:29], v[34:35], v[32:33] op_sel:[0,1,0]
	v_pk_fma_f32 v[22:23], v[22:23], v[36:37], v[26:27] op_sel_hi:[1,0,1]
	v_pk_fma_f32 v[24:25], v[24:25], v[36:37], v[28:29] op_sel_hi:[1,0,1]
	v_mov_b32_e32 v26, v37
	v_pk_fma_f32 v[18:19], v[18:19], v[26:27], v[22:23] op_sel_hi:[1,0,1]
	v_pk_fma_f32 v[20:21], v[20:21], v[26:27], v[24:25] op_sel_hi:[1,0,1]
	s_waitcnt lgkmcnt(0)
	v_pk_fma_f32 v[14:15], v[14:15], v[38:39], v[18:19] op_sel_hi:[1,0,1]
	v_pk_fma_f32 v[16:17], v[16:17], v[38:39], v[20:21] op_sel_hi:[1,0,1]
	v_pk_fma_f32 v[10:11], v[10:11], v[38:39], v[14:15] op_sel:[0,1,0]
	v_pk_fma_f32 v[12:13], v[12:13], v[38:39], v[16:17] op_sel:[0,1,0]
	v_pk_fma_f32 v[6:7], v[6:7], v[40:41], v[10:11] op_sel_hi:[1,0,1]
	v_pk_fma_f32 v[8:9], v[8:9], v[40:41], v[12:13] op_sel_hi:[1,0,1]
	v_mov_b32_e32 v10, v41
	v_pk_fma_f32 v[2:3], v[2:3], v[10:11], v[6:7] op_sel_hi:[1,0,1]
	v_pk_fma_f32 v[4:5], v[4:5], v[10:11], v[8:9] op_sel_hi:[1,0,1]
	v_cvt_pk_bf16_f32 v2, v2, v3
	s_nop 0
	v_cvt_pk_bf16_f32 v3, v4, v5
	v_or_b32_e32 v4, s91, v157
	v_ashrrev_i32_e32 v5, 31, v4
	v_lshlrev_b64 v[4:5], 13, v[4:5]
	v_lshl_add_u64 v[4:5], s[36:37], 0, v[4:5]
	v_lshl_add_u64 v[4:5], v[4:5], 0, s[22:23]
	v_lshl_add_u64 v[4:5], v[4:5], 0, v[134:135]
	global_store_dwordx2 v[4:5], v[2:3], off
	s_branch .LBB0_575

; __device__ __forceinline__ unsigned pk2(float lo, float hi) { unsigned r; asm("v_cvt_pk_bf16_f32 %0, %1, %2" : "=v"(r) : "v"(lo), "v"(hi)); return r; }
; __device__ __forceinline__ void ret_sample_item(Frame& F, int item) {
;     ...
;     if (fq < 2) {
; #pragma unroll
;         for (int j = 0; j < 4; ++j) { const int n = 4 * fq + j;
;             f32x4 o = (f32x4){oacc[0][j], oacc[1][j], oacc[2][j], oacc[3][j]} * gam;
; #pragma unroll
;             for (int m = 0; m < 8; ++m) o += pm[n * 8 + m] * v4[m];
;             u32x2 o2; o2.x = pk2(o[0], o[1]); o2.y = pk2(o[2], o[3]);
;             *(u32x2*)(WSP(bf16, WS_O) + (size_t)(r0 + n) * HV + h * DV + e4) = o2; }
;     }
.LBB0_677:
	s_and_saveexec_b64 s[58:59], s[8:9]
	s_cbranch_execz .LBB0_634
	s_nop 0
	ds_read_b128 v[34:37], v165 offset:34944
	ds_read_b128 v[38:41], v165 offset:34960
	v_mov_b32_e32 v42, v110
	v_mov_b32_e32 v43, v106
	s_lshl_b32 s18, s56, 1
	s_waitcnt lgkmcnt(1)
	v_pk_mul_f32 v[46:47], v[30:31], v[34:35] op_sel_hi:[1,0]
	v_pk_mul_f32 v[44:45], v[32:33], v[34:35] op_sel_hi:[1,0]
	v_pk_fma_f32 v[42:43], v[138:139], v[42:43], v[46:47] op_sel_hi:[0,1,1]
	v_mov_b32_e32 v46, v102
	v_mov_b32_e32 v47, v98
	v_pk_fma_f32 v[44:45], v[138:139], v[46:47], v[44:45] op_sel_hi:[0,1,1]
	v_pk_fma_f32 v[42:43], v[26:27], v[34:35], v[42:43] op_sel:[0,1,0]
	v_pk_fma_f32 v[34:35], v[28:29], v[34:35], v[44:45] op_sel:[0,1,0]
	v_pk_fma_f32 v[42:43], v[22:23], v[36:37], v[42:43] op_sel_hi:[1,0,1]
	v_pk_fma_f32 v[34:35], v[24:25], v[36:37], v[34:35] op_sel_hi:[1,0,1]
	v_mov_b32_e32 v36, v37
	v_pk_fma_f32 v[34:35], v[20:21], v[36:37], v[34:35] op_sel_hi:[1,0,1]
	v_pk_fma_f32 v[42:43], v[18:19], v[36:37], v[42:43] op_sel_hi:[1,0,1]
	s_waitcnt lgkmcnt(0)
	v_pk_fma_f32 v[34:35], v[16:17], v[38:39], v[34:35] op_sel_hi:[1,0,1]
	v_pk_fma_f32 v[36:37], v[14:15], v[38:39], v[42:43] op_sel_hi:[1,0,1]
	v_pk_fma_f32 v[34:35], v[12:13], v[38:39], v[34:35] op_sel:[0,1,0]
	v_pk_fma_f32 v[36:37], v[10:11], v[38:39], v[36:37] op_sel:[0,1,0]
	v_pk_fma_f32 v[34:35], v[8:9], v[40:41], v[34:35] op_sel_hi:[1,0,1]
	v_mov_b32_e32 v38, v41
	v_pk_fma_f32 v[36:37], v[6:7], v[40:41], v[36:37] op_sel_hi:[1,0,1]
	v_pk_fma_f32 v[34:35], v[4:5], v[38:39], v[34:35] op_sel_hi:[1,0,1]
	v_pk_fma_f32 v[36:37], v[2:3], v[38:39], v[36:37] op_sel_hi:[1,0,1]
	v_cvt_pk_bf16_f32 v39, v34, v35
	v_or_b32_e32 v34, s84, v154
	v_ashrrev_i32_e32 v35, 31, v34
	v_lshlrev_b64 v[34:35], 13, v[34:35]
	v_cvt_pk_bf16_f32 v38, v36, v37
	v_lshl_add_u64 v[40:41], s[20:21], 0, v[34:35]
	ds_read_b128 v[34:37], v166 offset:34944
	v_lshl_add_u64 v[40:41], v[40:41], 0, s[18:19]
	v_lshl_add_u64 v[40:41], v[40:41], 0, v[134:135]
	global_store_dwordx2 v[40:41], v[38:39], off
	ds_read_b128 v[38:41], v166 offset:34960
	s_waitcnt lgkmcnt(1)
	v_pk_mul_f32 v[42:43], v[32:33], v[34:35] op_sel_hi:[1,0]
	v_pk_mul_f32 v[44:45], v[30:31], v[34:35] op_sel_hi:[1,0]
	v_mov_b32_e32 v106, v111
	v_mov_b32_e32 v98, v103
	v_pk_fma_f32 v[44:45], v[138:139], v[106:107], v[44:45] op_sel_hi:[0,1,1]
	v_pk_fma_f32 v[42:43], v[138:139], v[98:99], v[42:43] op_sel_hi:[0,1,1]
	v_pk_fma_f32 v[44:45], v[26:27], v[34:35], v[44:45] op_sel:[0,1,0]
	v_pk_fma_f32 v[34:35], v[28:29], v[34:35], v[42:43] op_sel:[0,1,0]
	v_pk_fma_f32 v[42:43], v[22:23], v[36:37], v[44:45] op_sel_hi:[1,0,1]
	v_pk_fma_f32 v[34:35], v[24:25], v[36:37], v[34:35] op_sel_hi:[1,0,1]
	v_mov_b32_e32 v36, v37
	v_pk_fma_f32 v[34:35], v[20:21], v[36:37], v[34:35] op_sel_hi:[1,0,1]
	v_pk_fma_f32 v[42:43], v[18:19], v[36:37], v[42:43] op_sel_hi:[1,0,1]
	s_waitcnt lgkmcnt(0)
	v_pk_fma_f32 v[34:35], v[16:17], v[38:39], v[34:35] op_sel_hi:[1,0,1]
	v_pk_fma_f32 v[36:37], v[14:15], v[38:39], v[42:43] op_sel_hi:[1,0,1]
	v_pk_fma_f32 v[34:35], v[12:13], v[38:39], v[34:35] op_sel:[0,1,0]
	v_pk_fma_f32 v[36:37], v[10:11], v[38:39], v[36:37] op_sel:[0,1,0]
	v_pk_fma_f32 v[34:35], v[8:9], v[40:41], v[34:35] op_sel_hi:[1,0,1]
	v_mov_b32_e32 v38, v41
	v_pk_fma_f32 v[36:37], v[6:7], v[40:41], v[36:37] op_sel_hi:[1,0,1]
	v_pk_fma_f32 v[34:35], v[4:5], v[38:39], v[34:35] op_sel_hi:[1,0,1]
	v_pk_fma_f32 v[36:37], v[2:3], v[38:39], v[36:37] op_sel_hi:[1,0,1]
	v_cvt_pk_bf16_f32 v39, v34, v35
	v_or_b32_e32 v34, s84, v155
	v_ashrrev_i32_e32 v35, 31, v34
	v_lshlrev_b64 v[34:35], 13, v[34:35]
	v_cvt_pk_bf16_f32 v38, v36, v37
	v_lshl_add_u64 v[40:41], s[20:21], 0, v[34:35]
	ds_read_b128 v[34:37], v167 offset:34944
	v_lshl_add_u64 v[40:41], v[40:41], 0, s[18:19]
	v_lshl_add_u64 v[40:41], v[40:41], 0, v[134:135]
	global_store_dwordx2 v[40:41], v[38:39], off
	ds_read_b128 v[38:41], v167 offset:34960
	s_waitcnt lgkmcnt(1)
; __device__ __forceinline__ unsigned pk2(float lo, float hi) { unsigned r; asm("v_cvt_pk_bf16_f32 %0, %1, %2" : "=v"(r) : "v"(lo), "v"(hi)); return r; }
; __device__ __forceinline__ void ret_sample_item(Frame& F, int item) {
;     ...
;     if (fq < 2) {
; #pragma unroll
;         for (int j = 0; j < 4; ++j) { const int n = 4 * fq + j;
;             f32x4 o = (f32x4){oacc[0][j], oacc[1][j], oacc[2][j], oacc[3][j]} * gam;
; #pragma unroll
;             for (int m = 0; m < 8; ++m) o += pm[n * 8 + m] * v4[m];
;             u32x2 o2; o2.x = pk2(o[0], o[1]); o2.y = pk2(o[2], o[3]);
;             *(u32x2*)(WSP(bf16, WS_O) + (size_t)(r0 + n) * HV + h * DV + e4) = o2; }
;     }
	v_pk_mul_f32 v[44:45], v[30:31], v[34:35] op_sel_hi:[1,0]
	v_mov_b32_e32 v46, v112
	v_mov_b32_e32 v47, v108
	v_pk_mul_f32 v[42:43], v[32:33], v[34:35] op_sel_hi:[1,0]
	v_pk_fma_f32 v[44:45], v[138:139], v[46:47], v[44:45] op_sel_hi:[0,1,1]
	v_mov_b32_e32 v46, v104
	v_mov_b32_e32 v47, v100
	v_pk_fma_f32 v[42:43], v[138:139], v[46:47], v[42:43] op_sel_hi:[0,1,1]
	v_pk_fma_f32 v[44:45], v[26:27], v[34:35], v[44:45] op_sel:[0,1,0]
	v_pk_fma_f32 v[34:35], v[28:29], v[34:35], v[42:43] op_sel:[0,1,0]
	v_pk_fma_f32 v[42:43], v[22:23], v[36:37], v[44:45] op_sel_hi:[1,0,1]
	v_pk_fma_f32 v[34:35], v[24:25], v[36:37], v[34:35] op_sel_hi:[1,0,1]
	v_mov_b32_e32 v36, v37
	v_pk_fma_f32 v[34:35], v[20:21], v[36:37], v[34:35] op_sel_hi:[1,0,1]
	v_pk_fma_f32 v[42:43], v[18:19], v[36:37], v[42:43] op_sel_hi:[1,0,1]
	s_waitcnt lgkmcnt(0)
	v_pk_fma_f32 v[34:35], v[16:17], v[38:39], v[34:35] op_sel_hi:[1,0,1]
	v_pk_fma_f32 v[36:37], v[14:15], v[38:39], v[42:43] op_sel_hi:[1,0,1]
	v_pk_fma_f32 v[34:35], v[12:13], v[38:39], v[34:35] op_sel:[0,1,0]
	v_pk_fma_f32 v[36:37], v[10:11], v[38:39], v[36:37] op_sel:[0,1,0]
	v_pk_fma_f32 v[34:35], v[8:9], v[40:41], v[34:35] op_sel_hi:[1,0,1]
	v_mov_b32_e32 v38, v41
	v_pk_fma_f32 v[36:37], v[6:7], v[40:41], v[36:37] op_sel_hi:[1,0,1]
	v_pk_fma_f32 v[34:35], v[4:5], v[38:39], v[34:35] op_sel_hi:[1,0,1]
	v_pk_fma_f32 v[36:37], v[2:3], v[38:39], v[36:37] op_sel_hi:[1,0,1]
	v_cvt_pk_bf16_f32 v39, v34, v35
	v_or_b32_e32 v34, s84, v156
	v_ashrrev_i32_e32 v35, 31, v34
	v_lshlrev_b64 v[34:35], 13, v[34:35]
	v_cvt_pk_bf16_f32 v38, v36, v37
	v_lshl_add_u64 v[40:41], s[20:21], 0, v[34:35]
	ds_read_b128 v[34:37], v168 offset:34944
	v_lshl_add_u64 v[40:41], v[40:41], 0, s[18:19]
	v_lshl_add_u64 v[40:41], v[40:41], 0, v[134:135]
	global_store_dwordx2 v[40:41], v[38:39], off
	ds_read_b128 v[38:41], v168 offset:34960
	s_waitcnt lgkmcnt(1)
	v_pk_mul_f32 v[32:33], v[32:33], v[34:35] op_sel_hi:[1,0]
	v_pk_mul_f32 v[30:31], v[30:31], v[34:35] op_sel_hi:[1,0]
	v_mov_b32_e32 v108, v113
	v_mov_b32_e32 v100, v105
	v_pk_fma_f32 v[30:31], v[138:139], v[108:109], v[30:31] op_sel_hi:[0,1,1]
	v_pk_fma_f32 v[32:33], v[138:139], v[100:101], v[32:33] op_sel_hi:[0,1,1]
	v_pk_fma_f32 v[26:27], v[26:27], v[34:35], v[30:31] op_sel:[0,1,0]
	v_pk_fma_f32 v[28:29], v[28:29], v[34:35], v[32:33] op_sel:[0,1,0]
	v_pk_fma_f32 v[22:23], v[22:23], v[36:37], v[26:27] op_sel_hi:[1,0,1]
	v_pk_fma_f32 v[24:25], v[24:25], v[36:37], v[28:29] op_sel_hi:[1,0,1]
	v_mov_b32_e32 v26, v37
	v_pk_fma_f32 v[18:19], v[18:19], v[26:27], v[22:23] op_sel_hi:[1,0,1]
	v_pk_fma_f32 v[20:21], v[20:21], v[26:27], v[24:25] op_sel_hi:[1,0,1]
	s_waitcnt lgkmcnt(0)
	v_pk_fma_f32 v[14:15], v[14:15], v[38:39], v[18:19] op_sel_hi:[1,0,1]
	v_pk_fma_f32 v[16:17], v[16:17], v[38:39], v[20:21] op_sel_hi:[1,0,1]
	v_pk_fma_f32 v[10:11], v[10:11], v[38:39], v[14:15] op_sel:[0,1,0]
	v_pk_fma_f32 v[12:13], v[12:13], v[38:39], v[16:17] op_sel:[0,1,0]
	v_pk_fma_f32 v[6:7], v[6:7], v[40:41], v[10:11] op_sel_hi:[1,0,1]
	v_pk_fma_f32 v[8:9], v[8:9], v[40:41], v[12:13] op_sel_hi:[1,0,1]
	v_mov_b32_e32 v10, v41
	v_pk_fma_f32 v[2:3], v[2:3], v[10:11], v[6:7] op_sel_hi:[1,0,1]
	v_pk_fma_f32 v[4:5], v[4:5], v[10:11], v[8:9] op_sel_hi:[1,0,1]
	v_cvt_pk_bf16_f32 v2, v2, v3
	s_nop 0
	v_cvt_pk_bf16_f32 v3, v4, v5
	v_or_b32_e32 v4, s84, v157
	v_ashrrev_i32_e32 v5, 31, v4
	v_lshlrev_b64 v[4:5], 13, v[4:5]
	v_lshl_add_u64 v[4:5], s[20:21], 0, v[4:5]
	v_lshl_add_u64 v[4:5], v[4:5], 0, s[18:19]
	v_lshl_add_u64 v[4:5], v[4:5], 0, v[134:135]
	global_store_dwordx2 v[4:5], v[2:3], off
	s_branch .LBB0_634
